# chain LDS-DMA block: PD pieces 0-3 and VT pieces 0-3 share one M0 write each and step by the immediate offset (no per-piece m0 update, nop or offset VGPR)
# speedup vs baseline: 1.0063x; 1.0025x over previous
; DI void phase_gla_chain(const Params& P, int l, int task0, int ntask_stride, LAS unsigned char* lds) {
;     ...
;         __syncthreads();
;         CH_ISSUE(0, 0);
;         for (int n = 0; n < 64; ++n) {
;             const int b = n & 1;
;             if (n == 0) asm volatile("s_waitcnt vmcnt(0)" ::: "memory"); else asm volatile("s_waitcnt vmcnt(16)" ::: "memory");
;             __builtin_amdgcn_s_barrier();
;             asm volatile("" ::: "memory");
;             if (n + 1 < 64) CH_ISSUE(n + 1, b ^ 1);
.LBB0_410:
	s_add_i32 s91, s90, -1
	s_waitcnt vmcnt(16)
	s_barrier
	s_and_b32 s92, s91, 1
	s_cmp_eq_u32 s8, -1
	s_cbranch_scc1 .LBB0_409
	s_and_b64 s[22:23], s[10:11], exec
	s_cselect_b32 s22, s90, s8
	s_add_i32 s22, s22, s89
	s_lshl_b32 s22, s22, 2
	s_or_b32 s96, s22, s88
	s_ashr_i32 s97, s96, 31
	s_add_u32 s22, s25, s96
	s_addc_u32 s23, 0, s97
	s_mul_i32 s93, s23, 0xa000
	s_mul_hi_u32 vcc_lo, s22, 0xa000
	s_add_i32 vcc_lo, vcc_lo, s93
	s_mul_i32 s93, s22, 0xa000
	s_add_u32 vcc_hi, s27, s93
	s_addc_u32 vcc_lo, s28, vcc_lo
	s_lshl_b64 s[96:97], s[96:97], 15
	s_add_u32 s68, s29, s96
	s_addc_u32 s69, s30, s97
	s_xor_b32 s93, s92, 1
	s_mul_i32 s93, s93, 0x12400
	s_add_i32 s93, s93, 0
	v_add_u32_e32 v248, 0x1000, v134
	s_lshl_b32 s32, s31, 4
	s_lshl_b32 s98, s31, 2
	s_add_i32 s98, s98, s32
	s_add_u32 s100, vcc_hi, s98
	s_addc_u32 s101, vcc_lo, 0
	s_add_i32 s99, s93, s98
	s_add_i32 m0, s99, 0x0
	s_nop 0
	global_load_lds_dwordx4 v134, s[100:101] nt
	global_load_lds_dwordx4 v134, s[100:101] offset:1024 nt
	global_load_lds_dwordx4 v134, s[100:101] offset:2048 nt
	global_load_lds_dwordx4 v134, s[100:101] offset:3072 nt
	s_add_i32 m0, s99, 0x1000
	s_nop 0
	global_load_lds_dwordx4 v248, s[100:101] nt
	s_add_u32 s100, s68, s32
	s_addc_u32 s101, s69, 0
	s_add_i32 s99, s93, s32
	s_add_i32 m0, s99, 0xa000
	s_nop 0
	global_load_lds_dwordx4 v134, s[100:101] nt
	global_load_lds_dwordx4 v134, s[100:101] offset:1024 nt
	global_load_lds_dwordx4 v134, s[100:101] offset:2048 nt
	global_load_lds_dwordx4 v134, s[100:101] offset:3072 nt
	s_and_b64 vcc, exec, s[2:3]
	s_cbranch_vccnz .LBB0_409
	s_add_i32 s64, s93, s31
	s_lshl_b64 s[22:23], s[22:23], 9
	s_add_i32 m0, s64, 0x12000
	v_lshl_add_u64 v[66:67], v[156:157], 0, s[22:23]
	global_load_lds_dword v[66:67], off
	s_branch .LBB0_409

; DI void phase_gla_chain(const Params& P, int l, int task0, int ntask_stride, LAS unsigned char* lds) {
;     ...
;         __syncthreads();
;         CH_ISSUE(0, 0);
;         for (int n = 0; n < 64; ++n) {
;             const int b = n & 1;
;             if (n == 0) asm volatile("s_waitcnt vmcnt(0)" ::: "memory"); else asm volatile("s_waitcnt vmcnt(16)" ::: "memory");
;             __builtin_amdgcn_s_barrier();
;             asm volatile("" ::: "memory");
;             if (n + 1 < 64) CH_ISSUE(n + 1, b ^ 1);
.LBB0_972:
	s_add_i32 s83, s82, -1
	s_waitcnt vmcnt(16)
	s_barrier
	s_and_b32 s84, s83, 1
	s_cmp_eq_u32 s8, -1
	s_cbranch_scc1 .LBB0_971
	s_and_b64 s[22:23], s[10:11], exec
	s_cselect_b32 s22, s82, s8
	s_add_i32 s22, s22, s81
	s_lshl_b32 s22, s22, 2
	s_or_b32 s86, s22, s80
	s_ashr_i32 s87, s86, 31
	s_add_u32 s22, s25, s86
	s_addc_u32 s23, 0, s87
	s_mul_i32 s64, s23, 0xa000
	s_mul_hi_u32 s65, s22, 0xa000
	s_add_i32 s65, s65, s64
	s_mul_i32 s64, s22, 0xa000
	s_add_u32 s64, s27, s64
	s_addc_u32 s65, s28, s65
	s_lshl_b64 s[86:87], s[86:87], 15
	s_add_u32 s66, s29, s86
	s_addc_u32 s67, s30, s87
	s_xor_b32 s68, s84, 1
	s_mul_i32 s68, s68, 0x12400
	s_add_i32 s85, s68, 0
	v_add_u32_e32 v248, 0x1000, v134
	s_lshl_b32 s32, s31, 4
	s_lshl_b32 s98, s31, 2
	s_add_i32 s98, s98, s32
	s_add_u32 s100, s64, s98
	s_addc_u32 s101, s65, 0
	s_add_i32 s99, s85, s98
	s_add_i32 m0, s99, 0x0
	s_nop 0
	global_load_lds_dwordx4 v134, s[100:101] nt
	global_load_lds_dwordx4 v134, s[100:101] offset:1024 nt
	global_load_lds_dwordx4 v134, s[100:101] offset:2048 nt
	global_load_lds_dwordx4 v134, s[100:101] offset:3072 nt
	s_add_i32 m0, s99, 0x1000
	s_nop 0
	global_load_lds_dwordx4 v248, s[100:101] nt
	s_add_u32 s100, s66, s32
	s_addc_u32 s101, s67, 0
	s_add_i32 s99, s85, s32
	s_add_i32 m0, s99, 0xa000
	s_nop 0
	global_load_lds_dwordx4 v134, s[100:101] nt
	global_load_lds_dwordx4 v134, s[100:101] offset:1024 nt
	global_load_lds_dwordx4 v134, s[100:101] offset:2048 nt
	global_load_lds_dwordx4 v134, s[100:101] offset:3072 nt
	s_and_b64 vcc, exec, s[2:3]
	s_cbranch_vccnz .LBB0_971
	s_add_i32 s64, s85, s31
	s_lshl_b64 s[22:23], s[22:23], 9
	s_add_i32 m0, s64, 0x12000
	v_lshl_add_u64 v[66:67], v[156:157], 0, s[22:23]
	global_load_lds_dword v[66:67], off
	s_branch .LBB0_971
